# LN exchange arrival counters: one cache line per panel (placed in never-used zeroed padding of the barrier word array)
# baseline (speedup 1.0000x reference)
; DI void ln_exchange(const AccT& acc, LAS float* red, float* stats, unsigned* cnt, int pm, int pn, int tid, int wr, int wc, int fr, int fq) {
;     ...
;     float* sp = stats + ((size_t)(pm * 256 + tid) * 8 + pn) * 2;
;     __hip_atomic_store(sp, a, __ATOMIC_RELAXED, __HIP_MEMORY_SCOPE_AGENT); __hip_atomic_store(sp + 1, b, __ATOMIC_RELAXED, __HIP_MEMORY_SCOPE_AGENT); }
;   asm volatile("s_waitcnt vmcnt(0)" ::: "memory");
;   __syncthreads();
;   if (tid == 0) {
;     __builtin_amdgcn_fence(__ATOMIC_RELEASE, "agent");
;     asm volatile("s_waitcnt vmcnt(0)" ::: "memory");
;     __hip_atomic_fetch_add(cnt + pm, 1u, __ATOMIC_RELAXED, __HIP_MEMORY_SCOPE_AGENT);
;     unsigned sp_ = 0;
;     while (__hip_atomic_load(cnt + pm, __ATOMIC_RELAXED, __HIP_MEMORY_SCOPE_AGENT) < 8u) { __builtin_amdgcn_s_sleep(1); if (++sp_ > (1u << 24)) break; }
.LBB0_1803:
	s_or_b64 exec, exec, s[4:5]
	v_readlane_b32 s4, v252, 29
	s_lshl_b32 s72, s4, 2
	s_add_i32 s72, s72, 0x700
	s_lshl_b64 s[4:5], s[72:73], 2
	v_readlane_b32 s9, v249, 48
	s_waitcnt vmcnt(0)
	s_add_u32 s24, s9, s4
	v_readlane_b32 s4, v249, 49
	s_addc_u32 s25, s4, s5
	v_cmp_eq_u32_e64 s[4:5], 0, v166
	s_barrier
	s_and_saveexec_b64 s[14:15], s[4:5]
	s_cbranch_execz .LBB0_1820
	s_mov_b64 s[18:19], exec
	s_ashr_i32 s9, s8, 31
	s_waitcnt vmcnt(0)
	s_waitcnt vmcnt(0)
	s_lshr_b32 s17, s8, 4
	s_lshl_b32 s17, s17, 11
	s_lshl_b32 s16, s8, 7
	s_add_u32 s16, s16, s17
	s_mov_b32 s17, 0
	v_mbcnt_lo_u32_b32 v130, s18, 0
	s_add_u32 s16, s24, s16
	v_mbcnt_hi_u32_b32 v130, s19, v130
	s_addc_u32 s17, s25, s17
	v_cmp_eq_u32_e32 vcc, 0, v130
	s_and_saveexec_b64 s[20:21], vcc
	s_cbranch_execz .LBB0_1806
	s_bcnt1_i32_b64 s9, s[18:19]
	v_mov_b32_e32 v130, s9
	global_atomic_add v1, v130, s[16:17]

; DI void ln_exchange(const AccT& acc, LAS float* red, float* stats, unsigned* cnt, int pm, int pn, int tid, int wr, int wc, int fr, int fq) {
;     ...
;     float* sp = stats + ((size_t)(pm * 256 + tid) * 8 + pn) * 2;
;     __hip_atomic_store(sp, a, __ATOMIC_RELAXED, __HIP_MEMORY_SCOPE_AGENT); __hip_atomic_store(sp + 1, b, __ATOMIC_RELAXED, __HIP_MEMORY_SCOPE_AGENT); }
;   asm volatile("s_waitcnt vmcnt(0)" ::: "memory");
;   __syncthreads();
;   if (tid == 0) {
;     __builtin_amdgcn_fence(__ATOMIC_RELEASE, "agent");
;     asm volatile("s_waitcnt vmcnt(0)" ::: "memory");
;     __hip_atomic_fetch_add(cnt + pm, 1u, __ATOMIC_RELAXED, __HIP_MEMORY_SCOPE_AGENT);
;     unsigned sp_ = 0;
;     while (__hip_atomic_load(cnt + pm, __ATOMIC_RELAXED, __HIP_MEMORY_SCOPE_AGENT) < 8u) { __builtin_amdgcn_s_sleep(1); if (++sp_ > (1u << 24)) break; }
.LBB0_1840:
	s_or_b64 exec, exec, s[0:1]
	s_waitcnt vmcnt(0)
	s_barrier
	s_and_saveexec_b64 s[0:1], s[4:5]
	s_cbranch_execz .LBB0_1857
	s_ashr_i32 s9, s8, 31
	s_lshr_b32 s5, s8, 4
	s_lshl_b32 s5, s5, 11
	s_lshl_b32 s4, s8, 7
	s_add_u32 s4, s4, s5
	s_mov_b32 s5, 0
	s_mov_b64 s[8:9], exec
	s_waitcnt vmcnt(0)
	s_waitcnt vmcnt(0)
	v_mbcnt_lo_u32_b32 v0, s8, 0
	s_add_u32 s4, s24, s4
	v_mbcnt_hi_u32_b32 v0, s9, v0
	s_addc_u32 s5, s25, s5
	v_cmp_eq_u32_e32 vcc, 0, v0
	s_and_saveexec_b64 s[10:11], vcc
	s_cbranch_execz .LBB0_1843
	s_bcnt1_i32_b64 s8, s[8:9]
	v_mov_b32_e32 v0, s8
	global_atomic_add v1, v0, s[4:5] offset:4

; DI void ln_exchange(const AccT& acc, LAS float* red, float* stats, unsigned* cnt, int pm, int pn, int tid, int wr, int wc, int fr, int fq) {
;     ...
;     float* sp = stats + ((size_t)(pm * 256 + tid) * 8 + pn) * 2;
;     __hip_atomic_store(sp, a, __ATOMIC_RELAXED, __HIP_MEMORY_SCOPE_AGENT); __hip_atomic_store(sp + 1, b, __ATOMIC_RELAXED, __HIP_MEMORY_SCOPE_AGENT); }
;   asm volatile("s_waitcnt vmcnt(0)" ::: "memory");
;   __syncthreads();
;   if (tid == 0) {
;     __builtin_amdgcn_fence(__ATOMIC_RELEASE, "agent");
;     asm volatile("s_waitcnt vmcnt(0)" ::: "memory");
;     __hip_atomic_fetch_add(cnt + pm, 1u, __ATOMIC_RELAXED, __HIP_MEMORY_SCOPE_AGENT);
;     unsigned sp_ = 0;
;     while (__hip_atomic_load(cnt + pm, __ATOMIC_RELAXED, __HIP_MEMORY_SCOPE_AGENT) < 8u) { __builtin_amdgcn_s_sleep(1); if (++sp_ > (1u << 24)) break; }
.LBB0_2016:
	s_or_b64 exec, exec, s[4:5]
	s_lshl_b32 s72, s6, 1
	s_add_i32 s72, s72, 0x700
	s_lshl_b64 s[4:5], s[72:73], 2
	v_readlane_b32 s9, v249, 48
	s_waitcnt vmcnt(0)
	s_add_u32 s25, s9, s4
	v_readlane_b32 s4, v249, 49
	s_addc_u32 s26, s4, s5
	v_cmp_eq_u32_e64 s[4:5], 0, v220
	s_barrier
	s_and_saveexec_b64 s[14:15], s[4:5]
	s_cbranch_execz .LBB0_2033
	s_mov_b64 s[18:19], exec
	s_ashr_i32 s9, s8, 31
	s_waitcnt vmcnt(0)
	s_waitcnt vmcnt(0)
	s_lshr_b32 s17, s8, 4
	s_lshl_b32 s17, s17, 11
	s_lshl_b32 s16, s8, 7
	s_add_u32 s16, s16, s17
	s_mov_b32 s17, 0
	v_mbcnt_lo_u32_b32 v130, s18, 0
	s_add_u32 s16, s25, s16
	v_mbcnt_hi_u32_b32 v130, s19, v130
	s_addc_u32 s17, s26, s17
	v_cmp_eq_u32_e32 vcc, 0, v130
	s_and_saveexec_b64 s[20:21], vcc
	s_cbranch_execz .LBB0_2019
	s_bcnt1_i32_b64 s9, s[18:19]
	v_mov_b32_e32 v130, s9
	global_atomic_add v1, v130, s[16:17]

; DI void ln_exchange(const AccT& acc, LAS float* red, float* stats, unsigned* cnt, int pm, int pn, int tid, int wr, int wc, int fr, int fq) {
;     ...
;     float* sp = stats + ((size_t)(pm * 256 + tid) * 8 + pn) * 2;
;     __hip_atomic_store(sp, a, __ATOMIC_RELAXED, __HIP_MEMORY_SCOPE_AGENT); __hip_atomic_store(sp + 1, b, __ATOMIC_RELAXED, __HIP_MEMORY_SCOPE_AGENT); }
;   asm volatile("s_waitcnt vmcnt(0)" ::: "memory");
;   __syncthreads();
;   if (tid == 0) {
;     __builtin_amdgcn_fence(__ATOMIC_RELEASE, "agent");
;     asm volatile("s_waitcnt vmcnt(0)" ::: "memory");
;     __hip_atomic_fetch_add(cnt + pm, 1u, __ATOMIC_RELAXED, __HIP_MEMORY_SCOPE_AGENT);
;     unsigned sp_ = 0;
;     while (__hip_atomic_load(cnt + pm, __ATOMIC_RELAXED, __HIP_MEMORY_SCOPE_AGENT) < 8u) { __builtin_amdgcn_s_sleep(1); if (++sp_ > (1u << 24)) break; }
.LBB0_2054:
	s_or_b64 exec, exec, s[0:1]
	s_waitcnt vmcnt(0)
	s_barrier
	s_and_saveexec_b64 s[0:1], s[4:5]
	s_cbranch_execz .LBB0_2071
	s_ashr_i32 s9, s8, 31
	s_mov_b64 s[6:7], exec
	s_waitcnt vmcnt(0)
	s_waitcnt vmcnt(0)
	s_lshr_b32 s5, s8, 4
	s_lshl_b32 s5, s5, 11
	s_lshl_b32 s4, s8, 7
	s_add_u32 s4, s4, s5
	s_mov_b32 s5, 0
	v_mbcnt_lo_u32_b32 v0, s6, 0
	s_add_u32 s4, s25, s4
	v_mbcnt_hi_u32_b32 v0, s7, v0
	s_addc_u32 s5, s26, s5
	v_cmp_eq_u32_e32 vcc, 0, v0
	s_and_saveexec_b64 s[8:9], vcc
	s_cbranch_execz .LBB0_2057
	s_bcnt1_i32_b64 s6, s[6:7]
	v_mov_b32_e32 v0, s6
	global_atomic_add v1, v0, s[4:5] offset:4
